# NSA loops: mask fast path now branches right after the 5th QK MFMA, skipping the per-key compare operand set-up hipcc interleaves with the last QK MFMAs
# baseline (speedup 1.0000x reference)
.LBB0_1210:
	s_bitcmp1_b32 s16, 0
	v_lshrrev_b64 v[10:11], v0, v[170:171]
	s_cselect_b32 s27, 0x8c00, 0
	v_and_b32_e32 v10, 1, v10
	v_add_u32_e32 v234, s27, v219
	v_cmp_eq_u32_e32 vcc, 1, v10
	v_cmp_ne_u32_e64 s[0:1], 0, v10
	ds_read_b128 v[82:85], v234
	ds_read_b128 v[142:145], v234 offset:32
	ds_read_b128 v[138:141], v234 offset:64
	ds_read_b128 v[10:13], v234 offset:96
	s_cmp_lg_u64 s[0:1], 0
	s_cselect_b64 s[22:23], -1, 0
	s_and_b64 s[16:17], s[12:13], vcc
	v_lshl_or_b32 v233, v0, 6, v188
	v_cndmask_b32_e64 v169, 0, v168, s[16:17]
	v_add_u32_e32 v81, s27, v220
	s_mov_b64 vcc, s[0:1]
	s_cbranch_vccz .LBB0_1214
	s_waitcnt lgkmcnt(3)
	v_mfma_f32_32x32x16_bf16 v[82:97], v[82:85], v[122:125], 0
	s_waitcnt lgkmcnt(2)
	v_mfma_f32_32x32x16_bf16 v[82:97], v[142:145], v[126:129], v[82:97]
	s_waitcnt lgkmcnt(1)
	v_mfma_f32_32x32x16_bf16 v[82:97], v[138:141], v[98:101], v[82:97]
	ds_read_b128 v[138:141], v234 offset:128
	ds_read_b128 v[142:145], v234 offset:160
	ds_read_b128 v[236:239], v234 offset:192
	ds_read_b128 v[240:243], v234 offset:224
	s_waitcnt lgkmcnt(4)
	v_mfma_f32_32x32x16_bf16 v[82:97], v[10:13], v[102:105], v[82:97]
	s_waitcnt lgkmcnt(3)
	v_mfma_f32_32x32x16_bf16 v[82:97], v[138:141], v[106:109], v[82:97]
	s_cmp_eq_u64 s[14:15], 0
	s_cbranch_scc1 .Lself0
	v_cndmask_b32_e64 v0, v230, v233, s[16:17]
	v_cmp_le_u32_e32 vcc, v0, v169
	v_or_b32_e32 v208, 10, v0
	v_or_b32_e32 v209, 11, v0
	v_or_b32_e32 v210, 16, v0
	v_or_b32_e32 v211, 17, v0
	ds_read_b128 v[138:141], v81 offset:17408
	ds_read_b128 v[10:13], v81 offset:22016
	s_waitcnt lgkmcnt(4)
	v_mfma_f32_32x32x16_bf16 v[82:97], v[142:145], v[110:113], v[82:97]
	v_or_b32_e32 v142, 2, v0
	v_or_b32_e32 v143, 3, v0
	v_or_b32_e32 v144, 8, v0
	v_or_b32_e32 v145, 9, v0
	s_waitcnt lgkmcnt(3)
	v_mfma_f32_32x32x16_bf16 v[82:97], v[236:239], v[114:117], v[82:97]
	s_waitcnt lgkmcnt(2)
	v_mfma_f32_32x32x16_bf16 v[82:97], v[240:243], v[118:121], v[82:97]
	s_nop 11
	v_cndmask_b32_e32 v237, v231, v82, vcc
	v_cmp_lt_u32_e32 vcc, v0, v169
	v_or_b32_e32 v82, 18, v0
	s_nop 0
	v_cndmask_b32_e32 v238, v231, v83, vcc
	v_cmp_le_u32_e32 vcc, v142, v169
	s_nop 1
	v_cndmask_b32_e32 v239, v231, v84, vcc
	v_cmp_le_u32_e32 vcc, v143, v169
	s_nop 1
	v_cndmask_b32_e32 v240, v231, v85, vcc
	v_cmp_le_u32_e32 vcc, v144, v169
	s_nop 1
	v_cndmask_b32_e32 v142, v231, v86, vcc
	v_cmp_le_u32_e32 vcc, v145, v169
	s_nop 1
	v_cndmask_b32_e32 v143, v231, v87, vcc
	v_cmp_le_u32_e32 vcc, v208, v169
	s_nop 1
	v_cndmask_b32_e32 v144, v231, v88, vcc
	v_cmp_le_u32_e32 vcc, v209, v169
	s_nop 1
	v_cndmask_b32_e32 v145, v231, v89, vcc
	v_cmp_le_u32_e32 vcc, v210, v169
	s_nop 1
	v_cndmask_b32_e32 v244, v231, v90, vcc
	v_cmp_le_u32_e32 vcc, v211, v169
	s_nop 1
	v_cndmask_b32_e32 v241, v231, v91, vcc
	v_cmp_le_u32_e32 vcc, v82, v169
	v_or_b32_e32 v82, 19, v0
	s_nop 0
	v_cndmask_b32_e32 v242, v231, v92, vcc
	v_cmp_le_u32_e32 vcc, v82, v169
	v_or_b32_e32 v82, 24, v0
	s_nop 0
	v_cndmask_b32_e32 v243, v231, v93, vcc
	v_cmp_le_u32_e32 vcc, v82, v169
	v_or_b32_e32 v82, 25, v0
	s_nop 0
	v_cndmask_b32_e32 v90, v231, v94, vcc
	v_cmp_le_u32_e32 vcc, v82, v169
	v_or_b32_e32 v82, 26, v0
	v_or_b32_e32 v0, 27, v0
	v_cndmask_b32_e32 v91, v231, v95, vcc
	v_cmp_le_u32_e32 vcc, v82, v169
	v_max_f32_e32 v82, v237, v237
	s_nop 0
	v_cndmask_b32_e32 v92, v231, v96, vcc
	v_cmp_le_u32_e32 vcc, v0, v169
	v_max_f32_e32 v0, v238, v238
	v_max_f32_e32 v0, v82, v0
	v_max3_f32 v0, v0, v239, v240
	v_max3_f32 v0, v0, v142, v143
	v_max3_f32 v0, v0, v144, v145
	v_max3_f32 v0, v0, v244, v241
	v_max3_f32 v0, v0, v242, v243
	v_cndmask_b32_e32 v93, v231, v97, vcc
	v_max3_f32 v0, v0, v90, v91
	v_max3_f32 v0, v0, v92, v93

.Lself0:
	ds_read_b128 v[138:141], v81 offset:17408
	ds_read_b128 v[10:13], v81 offset:22016
	s_waitcnt lgkmcnt(4)
	v_mfma_f32_32x32x16_bf16 v[82:97], v[142:145], v[110:113], v[82:97]
	s_waitcnt lgkmcnt(3)
	v_mfma_f32_32x32x16_bf16 v[82:97], v[236:239], v[114:117], v[82:97]
	s_waitcnt lgkmcnt(2)
	v_mfma_f32_32x32x16_bf16 v[82:97], v[240:243], v[118:121], v[82:97]
	s_nop 11
	v_cndmask_b32_e64 v237, v231, v82, s[16:17]
	v_cndmask_b32_e64 v238, v231, v83, s[16:17]
	v_cndmask_b32_e64 v239, v231, v84, s[16:17]
	v_cndmask_b32_e64 v240, v231, v85, s[16:17]
	v_cndmask_b32_e64 v142, v231, v86, s[16:17]
	v_cndmask_b32_e64 v143, v231, v87, s[16:17]
	v_cndmask_b32_e64 v144, v231, v88, s[16:17]
	v_cndmask_b32_e64 v145, v231, v89, s[16:17]
	v_cndmask_b32_e64 v244, v231, v90, s[16:17]
	v_cndmask_b32_e64 v241, v231, v91, s[16:17]
	v_cndmask_b32_e64 v242, v231, v92, s[16:17]
	v_cndmask_b32_e64 v243, v231, v93, s[16:17]
	v_cndmask_b32_e64 v90, v231, v94, s[16:17]
	v_cndmask_b32_e64 v91, v231, v95, s[16:17]
	v_cndmask_b32_e64 v92, v231, v96, s[16:17]
	v_max_f32_e32 v0, v237, v238
	v_max3_f32 v0, v0, v239, v240
	v_max3_f32 v0, v0, v142, v143
	v_max3_f32 v0, v0, v144, v145
	v_max3_f32 v0, v0, v244, v241
	v_max3_f32 v0, v0, v242, v243
	v_cndmask_b32_e64 v93, v231, v97, s[16:17]
	v_max3_f32 v0, v0, v90, v91
	v_max3_f32 v0, v0, v92, v93
	s_branch .Lself0_join
.Lself1:
	s_waitcnt lgkmcnt(2)
	v_mfma_f32_32x32x16_bf16 v[82:97], v[142:145], v[110:113], v[82:97]
	ds_read_b128 v[138:141], v81 offset:17472
	ds_read_b128 v[10:13], v81 offset:22080
	s_waitcnt lgkmcnt(3)
	v_mfma_f32_32x32x16_bf16 v[82:97], v[238:241], v[114:117], v[82:97]
	s_waitcnt lgkmcnt(2)
	v_mfma_f32_32x32x16_bf16 v[82:97], v[242:245], v[118:121], v[82:97]
	s_nop 11
	v_cndmask_b32_e64 v144, v231, v82, s[16:17]
	v_cndmask_b32_e64 v145, v231, v83, s[16:17]
	v_cndmask_b32_e64 v233, v231, v84, s[16:17]
	v_cndmask_b32_e64 v234, v231, v85, s[16:17]
	v_cndmask_b32_e64 v14, v231, v86, s[16:17]
	v_cndmask_b32_e64 v15, v231, v87, s[16:17]
	v_cndmask_b32_e64 v142, v231, v88, s[16:17]
	v_cndmask_b32_e64 v143, v231, v89, s[16:17]
	v_cndmask_b32_e64 v237, v231, v90, s[16:17]
	v_cndmask_b32_e64 v238, v231, v91, s[16:17]
	v_cndmask_b32_e64 v239, v231, v92, s[16:17]
	v_cndmask_b32_e64 v240, v231, v93, s[16:17]
	v_cndmask_b32_e64 v90, v231, v94, s[16:17]
	v_cndmask_b32_e64 v91, v231, v95, s[16:17]
	v_cndmask_b32_e64 v92, v231, v96, s[16:17]
	v_max_f32_e32 v0, v144, v145
	v_max3_f32 v0, v0, v233, v234
	v_max3_f32 v0, v0, v14, v15
	v_max3_f32 v0, v0, v142, v143
	v_max3_f32 v0, v0, v237, v238
	v_max3_f32 v0, v0, v239, v240
	v_cndmask_b32_e64 v93, v231, v97, s[16:17]
	v_max3_f32 v0, v0, v90, v91
	v_max3_f32 v0, v0, v92, v93
	s_branch .Lself1_join

.LBB0_1217:
	s_andn2_b64 vcc, exec, s[22:23]
	s_cbranch_vccnz .LBB0_1221
	s_waitcnt lgkmcnt(3)
	v_mfma_f32_32x32x16_bf16 v[82:97], v[82:85], v[122:125], 0
	s_waitcnt lgkmcnt(2)
	v_mfma_f32_32x32x16_bf16 v[82:97], v[142:145], v[126:129], v[82:97]
	s_waitcnt lgkmcnt(1)
	v_mfma_f32_32x32x16_bf16 v[82:97], v[138:141], v[98:101], v[82:97]
	ds_read_b128 v[138:141], v234 offset:8832
	ds_read_b128 v[142:145], v234 offset:8864
	ds_read_b128 v[238:241], v234 offset:8896
	ds_read_b128 v[242:245], v234 offset:8928
	s_waitcnt lgkmcnt(4)
	v_mfma_f32_32x32x16_bf16 v[82:97], v[10:13], v[102:105], v[82:97]
	s_waitcnt lgkmcnt(3)
	v_mfma_f32_32x32x16_bf16 v[82:97], v[138:141], v[106:109], v[82:97]
	s_cmp_eq_u64 s[14:15], 0
	s_cbranch_scc1 .Lself1
	v_or_b32_e32 v0, 32, v233
	v_cndmask_b32_e64 v0, v230, v0, s[16:17]
	v_cmp_le_u32_e32 vcc, v0, v169
	v_or_b32_e32 v14, 2, v0
	v_or_b32_e32 v15, 3, v0
	v_or_b32_e32 v208, 10, v0
	v_or_b32_e32 v209, 11, v0
	s_waitcnt lgkmcnt(2)
	v_mfma_f32_32x32x16_bf16 v[82:97], v[142:145], v[110:113], v[82:97]
	v_or_b32_e32 v142, 8, v0
	v_or_b32_e32 v143, 9, v0
	v_or_b32_e32 v210, 16, v0
	ds_read_b128 v[138:141], v81 offset:17472
	ds_read_b128 v[10:13], v81 offset:22080
	s_waitcnt lgkmcnt(3)
	v_mfma_f32_32x32x16_bf16 v[82:97], v[238:241], v[114:117], v[82:97]
	s_waitcnt lgkmcnt(2)
	v_mfma_f32_32x32x16_bf16 v[82:97], v[242:245], v[118:121], v[82:97]
	s_nop 11
	v_cndmask_b32_e32 v144, v231, v82, vcc
	v_cmp_lt_u32_e32 vcc, v0, v169
	v_or_b32_e32 v82, 17, v0
	s_nop 0
	v_cndmask_b32_e32 v145, v231, v83, vcc
	v_cmp_le_u32_e32 vcc, v14, v169
	s_nop 1
	v_cndmask_b32_e32 v233, v231, v84, vcc
	v_cmp_le_u32_e32 vcc, v15, v169
	s_nop 1
	v_cndmask_b32_e32 v234, v231, v85, vcc
	v_cmp_le_u32_e32 vcc, v142, v169
	s_nop 1
	v_cndmask_b32_e32 v14, v231, v86, vcc
	v_cmp_le_u32_e32 vcc, v143, v169
	s_nop 1
	v_cndmask_b32_e32 v15, v231, v87, vcc
	v_cmp_le_u32_e32 vcc, v208, v169
	s_nop 1
	v_cndmask_b32_e32 v142, v231, v88, vcc
	v_cmp_le_u32_e32 vcc, v209, v169
	s_nop 1
	v_cndmask_b32_e32 v143, v231, v89, vcc
	v_cmp_le_u32_e32 vcc, v210, v169
	s_nop 1
	v_cndmask_b32_e32 v237, v231, v90, vcc
	v_cmp_le_u32_e32 vcc, v82, v169
	v_or_b32_e32 v82, 18, v0
	s_nop 0
	v_cndmask_b32_e32 v238, v231, v91, vcc
	v_cmp_le_u32_e32 vcc, v82, v169
	v_or_b32_e32 v82, 19, v0
	s_nop 0
	v_cndmask_b32_e32 v239, v231, v92, vcc
	v_cmp_le_u32_e32 vcc, v82, v169
	v_or_b32_e32 v82, 24, v0
	s_nop 0
	v_cndmask_b32_e32 v240, v231, v93, vcc
	v_cmp_le_u32_e32 vcc, v82, v169
	v_or_b32_e32 v82, 25, v0
	s_nop 0
	v_cndmask_b32_e32 v90, v231, v94, vcc
	v_cmp_le_u32_e32 vcc, v82, v169
	v_or_b32_e32 v82, 26, v0
	v_or_b32_e32 v0, 27, v0
	v_cndmask_b32_e32 v91, v231, v95, vcc
	v_cmp_le_u32_e32 vcc, v82, v169
	v_max_f32_e32 v82, v144, v144
	s_nop 0
	v_cndmask_b32_e32 v92, v231, v96, vcc
	v_cmp_le_u32_e32 vcc, v0, v169
	v_max_f32_e32 v0, v145, v145
	v_max_f32_e32 v0, v82, v0
	v_max3_f32 v0, v0, v233, v234
	v_max3_f32 v0, v0, v14, v15
	v_max3_f32 v0, v0, v142, v143
	v_max3_f32 v0, v0, v237, v238
	v_max3_f32 v0, v0, v239, v240
	v_cndmask_b32_e32 v93, v231, v97, vcc
	v_max3_f32 v0, v0, v90, v91
	v_max3_f32 v0, v0, v92, v93

.LBB0_1238:
	s_bitcmp1_b32 s15, 0
	s_cselect_b32 s0, 0x8c00, 0
	v_add_u32_e32 v245, s0, v219
	ds_read_b128 v[10:13], v245
	ds_read_b128 v[138:141], v245 offset:32
	v_add_u32_e32 v167, s0, v220
	v_lshl_add_u32 v172, v0, 6, v171
	s_waitcnt lgkmcnt(1)
	v_mfma_f32_32x32x16_bf16 v[80:95], v[10:13], v[122:125], 0
	s_waitcnt lgkmcnt(0)
	v_mfma_f32_32x32x16_bf16 v[80:95], v[138:141], v[126:129], v[80:95]
	ds_read_b128 v[10:13], v245 offset:64
	ds_read_b128 v[138:141], v245 offset:96
	s_waitcnt lgkmcnt(1)
	v_mfma_f32_32x32x16_bf16 v[80:95], v[10:13], v[98:101], v[80:95]
	ds_read_b128 v[10:13], v245 offset:128
	ds_read_b128 v[232:235], v245 offset:160
	ds_read_b128 v[236:239], v245 offset:192
	ds_read_b128 v[240:243], v245 offset:224
	s_waitcnt lgkmcnt(4)
	v_mfma_f32_32x32x16_bf16 v[80:95], v[138:141], v[102:105], v[80:95]
	s_waitcnt lgkmcnt(3)
	v_mfma_f32_32x32x16_bf16 v[80:95], v[10:13], v[106:109], v[80:95]
	s_cmp_eq_u64 s[12:13], 0
	s_cselect_b32 s98, s15, 0
	s_cmp_lg_u32 s98, 0
	s_cbranch_scc1 .Lwinf0
	s_movk_i32 s0, 0x200
	v_add_u32_e32 v0, 0xfffffe01, v172
	v_cmp_gt_u32_e32 vcc, s0, v172
	v_add_u32_e32 v145, 0xfffffe02, v172
	v_add_u32_e32 v173, 0xfffffe03, v172
	v_add_u32_e32 v174, 0xfffffe08, v172
	v_add_u32_e32 v175, 0xfffffe09, v172
	s_waitcnt lgkmcnt(2)
	v_mfma_f32_32x32x16_bf16 v[80:95], v[232:235], v[110:113], v[80:95]
	v_add_u32_e32 v208, 0xfffffe0a, v172
	v_add_u32_e32 v209, 0xfffffe0b, v172
	v_add_u32_e32 v210, 0xfffffe10, v172
	v_add_u32_e32 v211, 0xfffffe11, v172
	ds_read_b128 v[138:141], v167 offset:17408
	ds_read_b128 v[10:13], v167 offset:22016
	s_waitcnt lgkmcnt(3)
	v_mfma_f32_32x32x16_bf16 v[80:95], v[236:239], v[114:117], v[80:95]
	s_waitcnt lgkmcnt(2)
	v_mfma_f32_32x32x16_bf16 v[80:95], v[240:243], v[118:121], v[80:95]
	s_nop 11
	v_cndmask_b32_e32 v143, v231, v80, vcc
	v_cmp_lt_u32_e32 vcc, s87, v0
	v_add_u32_e32 v0, 0xfffffe12, v172
	v_max_f32_e32 v80, v143, v143
	v_cndmask_b32_e32 v144, v231, v81, vcc
	v_cmp_lt_u32_e32 vcc, s87, v145
	s_nop 1
	v_cndmask_b32_e32 v145, v231, v82, vcc
	v_cmp_lt_u32_e32 vcc, s87, v173
	s_nop 1
	v_cndmask_b32_e32 v232, v231, v83, vcc
	v_cmp_lt_u32_e32 vcc, s87, v174
	s_nop 1
	v_cndmask_b32_e32 v233, v231, v84, vcc
	v_cmp_lt_u32_e32 vcc, s87, v175
	s_nop 1
	v_cndmask_b32_e32 v234, v231, v85, vcc
	v_cmp_lt_u32_e32 vcc, s87, v208
	s_nop 1
	v_cndmask_b32_e32 v235, v231, v86, vcc
	v_cmp_lt_u32_e32 vcc, s87, v209
	s_nop 1
	v_cndmask_b32_e32 v236, v231, v87, vcc
	v_cmp_lt_u32_e32 vcc, s87, v210
	s_nop 1
	v_cndmask_b32_e32 v88, v231, v88, vcc
	v_cmp_lt_u32_e32 vcc, s87, v211
	s_nop 1
	v_cndmask_b32_e32 v89, v231, v89, vcc
	v_cmp_lt_u32_e32 vcc, s87, v0
	v_add_u32_e32 v0, 0xfffffe13, v172
	s_nop 0
	v_cndmask_b32_e32 v90, v231, v90, vcc
	v_cmp_lt_u32_e32 vcc, s87, v0
	v_add_u32_e32 v0, 0xfffffe18, v172
	s_nop 0
	v_cndmask_b32_e32 v91, v231, v91, vcc
	v_cmp_lt_u32_e32 vcc, s87, v0
	v_add_u32_e32 v0, 0xfffffe19, v172
	s_nop 0
	v_cndmask_b32_e32 v92, v231, v92, vcc
	v_cmp_lt_u32_e32 vcc, s87, v0
	v_add_u32_e32 v0, 0xfffffe1a, v172
	s_nop 0
	v_cndmask_b32_e32 v93, v231, v93, vcc
	v_cmp_lt_u32_e32 vcc, s87, v0
	v_add_u32_e32 v0, 0xfffffe1b, v172
	s_nop 0
	v_cndmask_b32_e32 v94, v231, v94, vcc
	v_cmp_lt_u32_e32 vcc, s87, v0
	v_max_f32_e32 v0, v144, v144
	v_max_f32_e32 v0, v80, v0
	v_max3_f32 v0, v0, v145, v232
	v_max3_f32 v0, v0, v233, v234
	v_max3_f32 v0, v0, v235, v236
	v_max3_f32 v0, v0, v88, v89
	v_max3_f32 v0, v0, v90, v91
	v_cndmask_b32_e32 v95, v231, v95, vcc
	v_max3_f32 v0, v0, v92, v93
	v_max3_f32 v0, v0, v94, v95

.LBB0_1242:
	s_waitcnt lgkmcnt(3)
	v_mfma_f32_32x32x16_bf16 v[80:95], v[80:83], v[122:125], 0
	s_waitcnt lgkmcnt(2)
	v_mfma_f32_32x32x16_bf16 v[80:95], v[142:145], v[126:129], v[80:95]
	s_waitcnt lgkmcnt(1)
	v_mfma_f32_32x32x16_bf16 v[80:95], v[138:141], v[98:101], v[80:95]
	ds_read_b128 v[138:141], v245 offset:8832
	ds_read_b128 v[142:145], v245 offset:8864
	ds_read_b128 v[248:251], v245 offset:8896
	ds_read_b128 v[208:211], v245 offset:8928
	s_waitcnt lgkmcnt(4)
	v_mfma_f32_32x32x16_bf16 v[80:95], v[10:13], v[102:105], v[80:95]
	s_waitcnt lgkmcnt(3)
	v_mfma_f32_32x32x16_bf16 v[80:95], v[138:141], v[106:109], v[80:95]
	s_cmp_eq_u64 s[12:13], 0
	s_cselect_b32 s98, s15, 1
	s_cmp_lg_u32 s98, 1
	s_cbranch_scc1 .Lwinf1
	v_add_u32_e32 v14, 0xfffffe20, v172
	v_cmp_lt_u32_e32 vcc, s87, v14
	v_add_u32_e32 v245, 0xfffffe28, v172
	v_add_u32_e32 v247, 0xfffffe29, v172
	v_add_u32_e32 v14, 0xfffffe31, v172
	ds_read_b128 v[138:141], v167 offset:17472
	ds_read_b128 v[10:13], v167 offset:22080
	s_waitcnt lgkmcnt(4)
	v_mfma_f32_32x32x16_bf16 v[80:95], v[142:145], v[110:113], v[80:95]
	v_add_u32_e32 v142, 0xfffffe21, v172
	v_add_u32_e32 v144, 0xfffffe22, v172
	v_add_u32_e32 v145, 0xfffffe23, v172
	s_waitcnt lgkmcnt(3)
	v_mfma_f32_32x32x16_bf16 v[80:95], v[248:251], v[114:117], v[80:95]
	v_add_u32_e32 v248, 0xfffffe2a, v172
	v_add_u32_e32 v249, 0xfffffe2b, v172
	v_add_u32_e32 v250, 0xfffffe30, v172
	s_waitcnt lgkmcnt(2)
	v_mfma_f32_32x32x16_bf16 v[80:95], v[208:211], v[118:121], v[80:95]
	s_nop 11
	v_cndmask_b32_e32 v15, v231, v80, vcc
	v_cmp_lt_u32_e32 vcc, s87, v142
	v_max_f32_e32 v80, v15, v15
	s_nop 0
	v_cndmask_b32_e32 v143, v231, v81, vcc
	v_cmp_lt_u32_e32 vcc, s87, v144
	s_nop 1
	v_cndmask_b32_e32 v144, v231, v82, vcc
	v_cmp_lt_u32_e32 vcc, s87, v145
	s_nop 1
	v_cndmask_b32_e32 v145, v231, v83, vcc
	v_cmp_lt_u32_e32 vcc, s87, v245
	s_nop 1
	v_cndmask_b32_e32 v245, v231, v84, vcc
	v_cmp_lt_u32_e32 vcc, s87, v247
	s_nop 1
	v_cndmask_b32_e32 v247, v231, v85, vcc
	v_cmp_lt_u32_e32 vcc, s87, v248
	s_nop 1
	v_cndmask_b32_e32 v248, v231, v86, vcc
	v_cmp_lt_u32_e32 vcc, s87, v249
	s_nop 1
	v_cndmask_b32_e32 v249, v231, v87, vcc
	v_cmp_lt_u32_e32 vcc, s87, v250
	s_nop 1
	v_cndmask_b32_e32 v88, v231, v88, vcc
	v_cmp_lt_u32_e32 vcc, s87, v14
	v_add_u32_e32 v14, 0xfffffe32, v172
	s_nop 0
	v_cndmask_b32_e32 v89, v231, v89, vcc
	v_cmp_lt_u32_e32 vcc, s87, v14
	v_add_u32_e32 v14, 0xfffffe33, v172
	s_nop 0
	v_cndmask_b32_e32 v90, v231, v90, vcc
	v_cmp_lt_u32_e32 vcc, s87, v14
	v_add_u32_e32 v14, 0xfffffe38, v172
	s_nop 0
	v_cndmask_b32_e32 v91, v231, v91, vcc
	v_cmp_lt_u32_e32 vcc, s87, v14
	v_add_u32_e32 v14, 0xfffffe39, v172
	s_nop 0
	v_cndmask_b32_e32 v92, v231, v92, vcc
	v_cmp_lt_u32_e32 vcc, s87, v14
	v_add_u32_e32 v14, 0xfffffe3a, v172
	s_nop 0
	v_cndmask_b32_e32 v93, v231, v93, vcc
	v_cmp_lt_u32_e32 vcc, s87, v14
	v_add_u32_e32 v14, 0xfffffe3b, v172
	s_nop 0
	v_cndmask_b32_e32 v94, v231, v94, vcc
	v_cmp_lt_u32_e32 vcc, s87, v14
	v_max_f32_e32 v14, v143, v143
	v_max_f32_e32 v14, v80, v14
	v_max3_f32 v14, v14, v144, v145
	v_max3_f32 v14, v14, v245, v247
	v_max3_f32 v14, v14, v248, v249
	v_max3_f32 v14, v14, v88, v89
	v_max3_f32 v14, v14, v90, v91
	v_cndmask_b32_e32 v95, v231, v95, vcc
	v_max3_f32 v14, v14, v92, v93
	v_max3_f32 v14, v14, v94, v95

.Lwinf0:
	s_waitcnt lgkmcnt(2)
	v_mfma_f32_32x32x16_bf16 v[80:95], v[232:235], v[110:113], v[80:95]
	ds_read_b128 v[138:141], v167 offset:17408
	ds_read_b128 v[10:13], v167 offset:22016
	s_waitcnt lgkmcnt(3)
	v_mfma_f32_32x32x16_bf16 v[80:95], v[236:239], v[114:117], v[80:95]
	s_waitcnt lgkmcnt(2)
	v_mfma_f32_32x32x16_bf16 v[80:95], v[240:243], v[118:121], v[80:95]
	s_nop 11
	v_mov_b32_e32 v143, v80
	v_mov_b32_e32 v144, v81
	v_mov_b32_e32 v145, v82
	v_mov_b32_e32 v232, v83
	v_mov_b32_e32 v233, v84
	v_mov_b32_e32 v234, v85
	v_mov_b32_e32 v235, v86
	v_mov_b32_e32 v236, v87
	v_max_f32_e32 v0, v143, v144
	v_max3_f32 v0, v0, v145, v232
	v_max3_f32 v0, v0, v233, v234
	v_max3_f32 v0, v0, v235, v236
	v_max3_f32 v0, v0, v88, v89
	v_max3_f32 v0, v0, v90, v91
	v_max3_f32 v0, v0, v92, v93
	v_max3_f32 v0, v0, v94, v95
	s_branch .Lwinf0_join
.Lwinf1:
	ds_read_b128 v[138:141], v167 offset:17472
	ds_read_b128 v[10:13], v167 offset:22080
	s_waitcnt lgkmcnt(4)
	v_mfma_f32_32x32x16_bf16 v[80:95], v[142:145], v[110:113], v[80:95]
	s_waitcnt lgkmcnt(3)
	v_mfma_f32_32x32x16_bf16 v[80:95], v[248:251], v[114:117], v[80:95]
	s_waitcnt lgkmcnt(2)
	v_mfma_f32_32x32x16_bf16 v[80:95], v[208:211], v[118:121], v[80:95]
	s_nop 11
	v_mov_b32_e32 v15, v80
	v_mov_b32_e32 v143, v81
	v_mov_b32_e32 v144, v82
	v_mov_b32_e32 v145, v83
	v_mov_b32_e32 v245, v84
	v_mov_b32_e32 v247, v85
	v_mov_b32_e32 v248, v86
	v_mov_b32_e32 v249, v87
	v_max_f32_e32 v14, v15, v143
	v_max3_f32 v14, v14, v144, v145
	v_max3_f32 v14, v14, v245, v247
	v_max3_f32 v14, v14, v248, v249
	v_max3_f32 v14, v14, v88, v89
	v_max3_f32 v14, v14, v90, v91
	v_max3_f32 v14, v14, v92, v93
	v_max3_f32 v14, v14, v94, v95
	s_branch .Lwinf1_join
